# v76 + P3 scan counted waits: batch-1 chunk waits count past the 45 newer hoisted loads, batch-2 chunk waits (store-ack pacing only) removed
# speedup vs baseline: 1.0077x; 1.0077x over previous
.LBB0_956:
	s_or_b64 exec, exec, s[4:5]
	v_ashrrev_i32_e32 v1, 4, v84
	v_lshl_add_u32 v232, s6, 5, v1
	v_lshlrev_b32_e32 v233, 4, v84
	s_ashr_i32 s1, s0, 31
	v_and_b32_e32 v85, 0xf0, v233
	s_lshl_b64 s[4:5], s[0:1], 12
	v_ashrrev_i32_e32 v233, 31, v232
	v_lshl_add_u64 v[234:235], s[4:5], 0, v[232:233]
	v_lshlrev_b64 v[234:235], 9, v[234:235]
	v_ashrrev_i32_e32 v232, 1, v232
	s_lshl_b64 s[8:9], s[0:1], 21
	v_bfi_b32 v232, -16, v232, v84
	v_lshl_add_u64 v[234:235], s[96:97], 0, v[234:235]
	v_lshlrev_b32_e32 v82, 1, v85
	v_mov_b32_e32 v83, 0
	s_add_u32 s8, s96, s8
	v_ashrrev_i32_e32 v233, 31, v232
	v_lshl_add_u64 v[88:89], v[234:235], 0, v[82:83]
	s_mov_b32 s7, 0x23b80000
	s_addc_u32 s9, s97, s9
	v_lshlrev_b64 v[232:233], 10, v[232:233]
	v_add_co_u32_e32 v234, vcc, s7, v88
	v_lshl_add_u64 v[232:233], s[8:9], 0, v[232:233]
	s_nop 0
	v_addc_co_u32_e32 v235, vcc, 0, v89, vcc
	s_mov_b64 s[8:9], 0x23b80000
	v_lshl_add_u64 v[234:235], v[88:89], 0, s[8:9]
	s_mov_b32 s7, 0x23ba0000
	v_add_co_u32_e32 v234, vcc, s7, v88
	v_and_b32_e32 v82, 0x1f0, v84
	s_mov_b64 s[8:9], 0x23ba0000
	v_addc_co_u32_e32 v235, vcc, 0, v89, vcc
	v_lshl_add_u64 v[86:87], v[232:233], 0, v[82:83]
	v_lshl_add_u64 v[232:233], v[88:89], 0, s[8:9]
	s_mov_b32 s7, 0x23bc0000
	v_add_co_u32_e32 v234, vcc, s7, v88
	s_mov_b64 s[8:9], 0x23bc0000
	s_nop 0
	v_addc_co_u32_e32 v235, vcc, 0, v89, vcc
	v_lshl_add_u64 v[232:233], v[88:89], 0, s[8:9]
	s_mov_b32 s7, 0x23be0000
	v_add_co_u32_e32 v234, vcc, s7, v88
	s_mov_b64 s[8:9], 0x23be0000
	s_nop 0
	v_addc_co_u32_e32 v235, vcc, 0, v89, vcc
	v_lshl_add_u64 v[232:233], v[88:89], 0, s[8:9]
	s_mov_b32 s7, 0x23c00000
	v_add_co_u32_e32 v234, vcc, s7, v88
	s_mov_b64 s[8:9], 0x23c00000
	s_nop 0
	v_addc_co_u32_e32 v235, vcc, 0, v89, vcc
	v_lshl_add_u64 v[232:233], v[88:89], 0, s[8:9]
	s_mov_b32 s7, 0x23c20000
	v_add_co_u32_e32 v234, vcc, s7, v88
	s_mov_b64 s[8:9], 0x23c20000
	s_nop 0
	v_addc_co_u32_e32 v235, vcc, 0, v89, vcc
	v_lshl_add_u64 v[232:233], v[88:89], 0, s[8:9]
	s_mov_b32 s7, 0x23c40000
	v_add_co_u32_e32 v234, vcc, s7, v88
	s_mov_b64 s[8:9], 0x23c40000
	s_nop 0
	v_addc_co_u32_e32 v235, vcc, 0, v89, vcc
	v_lshl_add_u64 v[232:233], v[88:89], 0, s[8:9]
	s_mov_b32 s7, 0x23c60000
	v_add_co_u32_e32 v240, vcc, s7, v88
	s_mov_b64 s[8:9], 0x23c60000
	s_nop 0
	v_addc_co_u32_e32 v241, vcc, 0, v89, vcc
	v_lshl_add_u64 v[242:243], v[88:89], 0, s[8:9]
	ds_read_b128 v[54:57], v83
	ds_read_b128 v[58:61], v83 offset:64
	ds_read_b128 v[66:69], v83 offset:16
	s_mov_b32 s7, 0x27ba0000
	v_add_co_u32_e32 v102, vcc, s7, v86
	s_waitcnt lgkmcnt(2)
	v_mul_f32_e32 v82, 0, v54
	v_addc_co_u32_e32 v103, vcc, 0, v87, vcc
	s_mov_b32 s7, 0x27bc0000
	ds_read_b128 v[70:73], v83 offset:80
	s_mov_b64 s[8:9], 0x23c80000
	v_lshlrev_b32_e32 v1, 2, v1
	v_readlane_b32 s36, v245, 25
	v_readlane_b32 s50, v245, 39
	v_readlane_b32 s51, v245, 40
	s_movk_i32 s10, 0x84
	v_readlane_b32 s37, v245, 26
	v_readlane_b32 s38, v245, 27
	v_readlane_b32 s39, v245, 28
	s_waitcnt vmcnt(60)
	v_lshlrev_b32_e32 v90, 16, v78
	v_and_b32_e32 v91, 0xffff0000, v78
	s_waitcnt vmcnt(59)
	v_lshlrev_b32_e32 v94, 16, v74
	v_and_b32_e32 v95, 0xffff0000, v74
	v_lshlrev_b32_e32 v74, 16, v75
	v_and_b32_e32 v75, 0xffff0000, v75
	v_lshlrev_b32_e32 v78, 16, v79
	v_and_b32_e32 v79, 0xffff0000, v79
	v_lshlrev_b32_e32 v92, 16, v80
	v_and_b32_e32 v93, 0xffff0000, v80
	v_lshlrev_b32_e32 v80, 16, v81
	v_and_b32_e32 v81, 0xffff0000, v81
	s_waitcnt lgkmcnt(2)
	v_pk_fma_f32 v[96:97], v[58:59], v[74:75], v[82:83] op_sel_hi:[0,1,0]
	v_lshlrev_b32_e32 v74, 16, v76
	v_and_b32_e32 v75, 0xffff0000, v76
	v_pk_fma_f32 v[90:91], v[58:59], v[90:91], v[82:83] op_sel_hi:[0,1,0]
	v_pk_fma_f32 v[78:79], v[58:59], v[78:79], v[82:83] op_sel_hi:[0,1,0]
	v_pk_fma_f32 v[92:93], v[58:59], v[92:93], v[82:83] op_sel_hi:[0,1,0]
	v_pk_fma_f32 v[80:81], v[58:59], v[80:81], v[82:83] op_sel_hi:[0,1,0]
	v_pk_fma_f32 v[98:99], v[58:59], v[74:75], v[82:83] op_sel_hi:[0,1,0]
	v_lshlrev_b32_e32 v74, 16, v77
	v_and_b32_e32 v75, 0xffff0000, v77
	v_pk_fma_f32 v[94:95], v[58:59], v[94:95], v[82:83] op_sel_hi:[0,1,0]
	v_pk_fma_f32 v[100:101], v[58:59], v[74:75], v[82:83] op_sel_hi:[0,1,0]
	v_cvt_pk_bf16_f32 v74, v90, v91
	v_cvt_pk_bf16_f32 v75, v78, v79
	v_cvt_pk_bf16_f32 v76, v92, v93
	v_cvt_pk_bf16_f32 v77, v80, v81
	global_store_dwordx4 v[102:103], v[74:77], off
	v_readlane_b32 s40, v245, 29
	v_readlane_b32 s41, v245, 30
	v_cvt_pk_bf16_f32 v74, v94, v95
	v_cvt_pk_bf16_f32 v75, v96, v97
	v_cvt_pk_bf16_f32 v76, v98, v99
	v_cvt_pk_bf16_f32 v77, v100, v101
	global_store_dwordx4 v[102:103], v[74:77], off offset:512
	v_readlane_b32 s42, v245, 31
	v_readlane_b32 s43, v245, 32
	s_waitcnt vmcnt(60)
	v_lshlrev_b32_e32 v74, 16, v62
	v_and_b32_e32 v75, 0xffff0000, v62
	v_lshlrev_b32_e32 v62, 16, v63
	v_and_b32_e32 v63, 0xffff0000, v63
	v_pk_mul_f32 v[62:63], v[58:59], v[62:63] op_sel:[1,0]
	v_lshlrev_b32_e32 v76, 16, v64
	v_pk_fma_f32 v[62:63], v[78:79], v[54:55], v[62:63] op_sel:[0,1,0]
	v_and_b32_e32 v77, 0xffff0000, v64
	v_lshlrev_b32_e32 v64, 16, v65
	v_and_b32_e32 v65, 0xffff0000, v65
	s_waitcnt vmcnt(59)
	v_lshlrev_b32_e32 v78, 16, v50
	v_and_b32_e32 v79, 0xffff0000, v50
	v_lshlrev_b32_e32 v50, 16, v51
	v_and_b32_e32 v51, 0xffff0000, v51
	v_pk_mul_f32 v[64:65], v[58:59], v[64:65] op_sel:[1,0]
	v_pk_mul_f32 v[50:51], v[58:59], v[50:51] op_sel:[1,0]
	v_pk_fma_f32 v[64:65], v[80:81], v[54:55], v[64:65] op_sel:[0,1,0]
	v_pk_fma_f32 v[80:81], v[96:97], v[54:55], v[50:51] op_sel:[0,1,0]
	v_lshlrev_b32_e32 v50, 16, v52
	v_and_b32_e32 v51, 0xffff0000, v52
	v_pk_mul_f32 v[74:75], v[58:59], v[74:75] op_sel:[1,0]
	v_pk_mul_f32 v[50:51], v[58:59], v[50:51] op_sel:[1,0]
	v_pk_fma_f32 v[74:75], v[90:91], v[54:55], v[74:75] op_sel:[0,1,0]
	v_pk_mul_f32 v[76:77], v[58:59], v[76:77] op_sel:[1,0]
	v_pk_fma_f32 v[90:91], v[98:99], v[54:55], v[50:51] op_sel:[0,1,0]
	v_lshlrev_b32_e32 v50, 16, v53
	v_and_b32_e32 v51, 0xffff0000, v53
	v_pk_fma_f32 v[76:77], v[92:93], v[54:55], v[76:77] op_sel:[0,1,0]
	v_pk_mul_f32 v[78:79], v[58:59], v[78:79] op_sel:[1,0]
	v_pk_mul_f32 v[50:51], v[58:59], v[50:51] op_sel:[1,0]
	v_add_co_u32_e32 v58, vcc, s7, v86
	v_pk_fma_f32 v[78:79], v[94:95], v[54:55], v[78:79] op_sel:[0,1,0]
	v_pk_fma_f32 v[54:55], v[100:101], v[54:55], v[50:51] op_sel:[0,1,0]
	v_cvt_pk_bf16_f32 v50, v74, v75
	v_cvt_pk_bf16_f32 v51, v62, v63
	v_cvt_pk_bf16_f32 v52, v76, v77
	v_cvt_pk_bf16_f32 v53, v64, v65
	v_addc_co_u32_e32 v59, vcc, 0, v87, vcc
	global_store_dwordx4 v[58:59], v[50:53], off
	s_mov_b32 s7, 0x27be0000
	v_readlane_b32 s44, v245, 33
	v_cvt_pk_bf16_f32 v50, v78, v79
	v_cvt_pk_bf16_f32 v51, v80, v81
	v_cvt_pk_bf16_f32 v52, v90, v91
	v_cvt_pk_bf16_f32 v53, v54, v55
	global_store_dwordx4 v[58:59], v[50:53], off offset:512
	s_waitcnt vmcnt(59)
	v_lshlrev_b32_e32 v58, 16, v42
	v_and_b32_e32 v59, 0xffff0000, v42
	v_lshlrev_b32_e32 v50, 16, v46
	v_and_b32_e32 v51, 0xffff0000, v46
	v_lshlrev_b32_e32 v46, 16, v47
	v_and_b32_e32 v47, 0xffff0000, v47
	v_lshlrev_b32_e32 v42, 16, v43
	v_and_b32_e32 v43, 0xffff0000, v43
	v_pk_mul_f32 v[46:47], v[60:61], v[46:47] op_sel_hi:[0,1]
	v_pk_mul_f32 v[42:43], v[60:61], v[42:43] op_sel_hi:[0,1]
	v_pk_fma_f32 v[46:47], v[62:63], v[56:57], v[46:47] op_sel_hi:[1,0,1]
	v_lshlrev_b32_e32 v52, 16, v48
	v_and_b32_e32 v53, 0xffff0000, v48
	v_lshlrev_b32_e32 v48, 16, v49
	v_and_b32_e32 v49, 0xffff0000, v49
	v_pk_fma_f32 v[62:63], v[80:81], v[56:57], v[42:43] op_sel_hi:[1,0,1]
	v_lshlrev_b32_e32 v42, 16, v44
	v_and_b32_e32 v43, 0xffff0000, v44
	v_pk_mul_f32 v[48:49], v[60:61], v[48:49] op_sel_hi:[0,1]
	v_pk_mul_f32 v[42:43], v[60:61], v[42:43] op_sel_hi:[0,1]
	v_pk_mul_f32 v[50:51], v[60:61], v[50:51] op_sel_hi:[0,1]
	v_pk_mul_f32 v[52:53], v[60:61], v[52:53] op_sel_hi:[0,1]
	v_pk_fma_f32 v[48:49], v[64:65], v[56:57], v[48:49] op_sel_hi:[1,0,1]
	v_pk_fma_f32 v[64:65], v[90:91], v[56:57], v[42:43] op_sel_hi:[1,0,1]
	v_lshlrev_b32_e32 v42, 16, v45
	v_and_b32_e32 v43, 0xffff0000, v45
	v_pk_fma_f32 v[50:51], v[74:75], v[56:57], v[50:51] op_sel_hi:[1,0,1]
	v_pk_fma_f32 v[52:53], v[76:77], v[56:57], v[52:53] op_sel_hi:[1,0,1]
	v_pk_mul_f32 v[58:59], v[60:61], v[58:59] op_sel_hi:[0,1]
	v_pk_mul_f32 v[42:43], v[60:61], v[42:43] op_sel_hi:[0,1]
	v_add_co_u32_e32 v74, vcc, s7, v86
	v_pk_fma_f32 v[58:59], v[78:79], v[56:57], v[58:59] op_sel_hi:[1,0,1]
	v_pk_fma_f32 v[54:55], v[54:55], v[56:57], v[42:43] op_sel_hi:[1,0,1]
	v_cvt_pk_bf16_f32 v42, v50, v51
	v_cvt_pk_bf16_f32 v43, v46, v47
	v_cvt_pk_bf16_f32 v44, v52, v53
	v_cvt_pk_bf16_f32 v45, v48, v49
	v_addc_co_u32_e32 v75, vcc, 0, v87, vcc
	global_store_dwordx4 v[74:75], v[42:45], off
	s_mov_b32 s7, 0x27c00000
	v_readlane_b32 s45, v245, 34
	v_cvt_pk_bf16_f32 v42, v58, v59
	v_cvt_pk_bf16_f32 v43, v62, v63
	v_cvt_pk_bf16_f32 v44, v64, v65
	v_cvt_pk_bf16_f32 v45, v54, v55
	global_store_dwordx4 v[74:75], v[42:45], off offset:512
	v_readlane_b32 s46, v245, 35
	v_readlane_b32 s47, v245, 36
	s_waitcnt vmcnt(60)
	v_lshlrev_b32_e32 v44, 16, v38
	v_and_b32_e32 v45, 0xffff0000, v38
	v_mov_b32_e32 v38, v61
	v_mov_b32_e32 v42, v57
	v_pk_mul_f32 v[44:45], v[38:39], v[44:45] op_sel_hi:[0,1]
	v_pk_fma_f32 v[44:45], v[50:51], v[42:43], v[44:45] op_sel_hi:[1,0,1]
	v_lshlrev_b32_e32 v50, 16, v39
	v_and_b32_e32 v51, 0xffff0000, v39
	v_pk_mul_f32 v[50:51], v[38:39], v[50:51] op_sel_hi:[0,1]
	v_pk_fma_f32 v[46:47], v[46:47], v[42:43], v[50:51] op_sel_hi:[1,0,1]
	v_lshlrev_b32_e32 v50, 16, v40
	v_and_b32_e32 v51, 0xffff0000, v40
	v_lshlrev_b32_e32 v40, 16, v41
	v_and_b32_e32 v41, 0xffff0000, v41
	v_pk_mul_f32 v[40:41], v[38:39], v[40:41] op_sel_hi:[0,1]
	v_pk_fma_f32 v[40:41], v[48:49], v[42:43], v[40:41] op_sel_hi:[1,0,1]
	s_waitcnt vmcnt(59)
	v_lshlrev_b32_e32 v48, 16, v34
	v_and_b32_e32 v49, 0xffff0000, v34
	v_lshlrev_b32_e32 v34, 16, v35
	v_and_b32_e32 v35, 0xffff0000, v35
	v_pk_mul_f32 v[50:51], v[38:39], v[50:51] op_sel_hi:[0,1]
	v_pk_mul_f32 v[34:35], v[38:39], v[34:35] op_sel_hi:[0,1]
	v_pk_fma_f32 v[50:51], v[52:53], v[42:43], v[50:51] op_sel_hi:[1,0,1]
	v_pk_fma_f32 v[52:53], v[62:63], v[42:43], v[34:35] op_sel_hi:[1,0,1]
	v_lshlrev_b32_e32 v34, 16, v36
	v_and_b32_e32 v35, 0xffff0000, v36
	v_pk_mul_f32 v[34:35], v[38:39], v[34:35] op_sel_hi:[0,1]
	v_pk_fma_f32 v[56:57], v[64:65], v[42:43], v[34:35] op_sel_hi:[1,0,1]
	v_lshlrev_b32_e32 v34, 16, v37
	v_and_b32_e32 v35, 0xffff0000, v37
	v_pk_mul_f32 v[48:49], v[38:39], v[48:49] op_sel_hi:[0,1]
	v_pk_mul_f32 v[34:35], v[38:39], v[34:35] op_sel_hi:[0,1]
	v_pk_fma_f32 v[48:49], v[58:59], v[42:43], v[48:49] op_sel_hi:[1,0,1]
	v_pk_fma_f32 v[38:39], v[54:55], v[42:43], v[34:35] op_sel_hi:[1,0,1]
	v_add_co_u32_e32 v42, vcc, s7, v86
	v_cvt_pk_bf16_f32 v34, v44, v45
	v_cvt_pk_bf16_f32 v35, v46, v47
	v_cvt_pk_bf16_f32 v36, v50, v51
	v_cvt_pk_bf16_f32 v37, v40, v41
	v_addc_co_u32_e32 v43, vcc, 0, v87, vcc
	global_store_dwordx4 v[42:43], v[34:37], off
	s_mov_b32 s7, 0x27c20000
	v_readlane_b32 s48, v245, 37
	v_cvt_pk_bf16_f32 v34, v48, v49
	v_cvt_pk_bf16_f32 v35, v52, v53
	v_cvt_pk_bf16_f32 v36, v56, v57
	v_cvt_pk_bf16_f32 v37, v38, v39
	global_store_dwordx4 v[42:43], v[34:37], off offset:512
	v_readlane_b32 s49, v245, 38
	s_waitcnt vmcnt(60)
	v_lshlrev_b32_e32 v36, 16, v32
	v_and_b32_e32 v37, 0xffff0000, v32
	v_lshlrev_b32_e32 v32, 16, v33
	v_and_b32_e32 v33, 0xffff0000, v33
	s_waitcnt lgkmcnt(0)
	v_pk_mul_f32 v[32:33], v[70:71], v[32:33] op_sel_hi:[0,1]
	v_pk_fma_f32 v[32:33], v[40:41], v[66:67], v[32:33] op_sel_hi:[1,0,1]
	s_waitcnt vmcnt(59)
	v_lshlrev_b32_e32 v40, 16, v26
	v_and_b32_e32 v41, 0xffff0000, v26
	v_lshlrev_b32_e32 v26, 16, v27
	v_and_b32_e32 v27, 0xffff0000, v27
	v_pk_mul_f32 v[26:27], v[70:71], v[26:27] op_sel_hi:[0,1]
	v_lshlrev_b32_e32 v34, 16, v30
	v_and_b32_e32 v35, 0xffff0000, v30
	v_pk_fma_f32 v[42:43], v[52:53], v[66:67], v[26:27] op_sel_hi:[1,0,1]
	v_lshlrev_b32_e32 v26, 16, v28
	v_and_b32_e32 v27, 0xffff0000, v28
	v_pk_mul_f32 v[34:35], v[70:71], v[34:35] op_sel_hi:[0,1]
	v_lshlrev_b32_e32 v30, 16, v31
	v_and_b32_e32 v31, 0xffff0000, v31
	v_pk_mul_f32 v[26:27], v[70:71], v[26:27] op_sel_hi:[0,1]
	v_pk_fma_f32 v[34:35], v[44:45], v[66:67], v[34:35] op_sel_hi:[1,0,1]
	v_pk_mul_f32 v[30:31], v[70:71], v[30:31] op_sel_hi:[0,1]
	v_pk_mul_f32 v[36:37], v[70:71], v[36:37] op_sel_hi:[0,1]
	v_pk_fma_f32 v[44:45], v[56:57], v[66:67], v[26:27] op_sel_hi:[1,0,1]
	v_lshlrev_b32_e32 v26, 16, v29
	v_and_b32_e32 v27, 0xffff0000, v29
	v_pk_fma_f32 v[30:31], v[46:47], v[66:67], v[30:31] op_sel_hi:[1,0,1]
	v_pk_fma_f32 v[36:37], v[50:51], v[66:67], v[36:37] op_sel_hi:[1,0,1]
	v_pk_mul_f32 v[40:41], v[70:71], v[40:41] op_sel_hi:[0,1]
	v_pk_mul_f32 v[26:27], v[70:71], v[26:27] op_sel_hi:[0,1]
	v_add_co_u32_e32 v46, vcc, s7, v86
	v_pk_fma_f32 v[40:41], v[48:49], v[66:67], v[40:41] op_sel_hi:[1,0,1]
	v_pk_fma_f32 v[38:39], v[38:39], v[66:67], v[26:27] op_sel_hi:[1,0,1]
	v_cvt_pk_bf16_f32 v26, v34, v35
	v_cvt_pk_bf16_f32 v27, v30, v31
	v_cvt_pk_bf16_f32 v28, v36, v37
	v_cvt_pk_bf16_f32 v29, v32, v33
	v_addc_co_u32_e32 v47, vcc, 0, v87, vcc
	global_store_dwordx4 v[46:47], v[26:29], off
	s_mov_b32 s7, 0x27c40000
	s_nop 0
	v_cvt_pk_bf16_f32 v26, v40, v41
	v_cvt_pk_bf16_f32 v27, v42, v43
	v_cvt_pk_bf16_f32 v28, v44, v45
	v_cvt_pk_bf16_f32 v29, v38, v39
	global_store_dwordx4 v[46:47], v[26:29], off offset:512
	s_waitcnt vmcnt(60)
	s_nop 0
	v_lshlrev_b32_e32 v26, 16, v22
	v_and_b32_e32 v27, 0xffff0000, v22
	v_lshlrev_b32_e32 v22, 16, v23
	v_and_b32_e32 v23, 0xffff0000, v23
	v_pk_mul_f32 v[22:23], v[70:71], v[22:23] op_sel:[1,0]
	v_lshlrev_b32_e32 v28, 16, v24
	v_pk_fma_f32 v[22:23], v[30:31], v[66:67], v[22:23] op_sel:[0,1,0]
	v_and_b32_e32 v29, 0xffff0000, v24
	v_lshlrev_b32_e32 v24, 16, v25
	v_and_b32_e32 v25, 0xffff0000, v25
	s_waitcnt vmcnt(59)
	v_lshlrev_b32_e32 v30, 16, v18
	v_and_b32_e32 v31, 0xffff0000, v18
	v_lshlrev_b32_e32 v18, 16, v19
	v_and_b32_e32 v19, 0xffff0000, v19
	v_pk_mul_f32 v[24:25], v[70:71], v[24:25] op_sel:[1,0]
	v_pk_mul_f32 v[18:19], v[70:71], v[18:19] op_sel:[1,0]
	v_pk_fma_f32 v[24:25], v[32:33], v[66:67], v[24:25] op_sel:[0,1,0]
	v_pk_fma_f32 v[32:33], v[42:43], v[66:67], v[18:19] op_sel:[0,1,0]
	v_lshlrev_b32_e32 v18, 16, v20
	v_and_b32_e32 v19, 0xffff0000, v20
	v_pk_mul_f32 v[26:27], v[70:71], v[26:27] op_sel:[1,0]
	v_pk_mul_f32 v[18:19], v[70:71], v[18:19] op_sel:[1,0]
	v_pk_fma_f32 v[26:27], v[34:35], v[66:67], v[26:27] op_sel:[0,1,0]
	v_pk_fma_f32 v[34:35], v[44:45], v[66:67], v[18:19] op_sel:[0,1,0]
	v_lshlrev_b32_e32 v18, 16, v21
	v_and_b32_e32 v19, 0xffff0000, v21
	v_pk_mul_f32 v[28:29], v[70:71], v[28:29] op_sel:[1,0]
	v_pk_mul_f32 v[18:19], v[70:71], v[18:19] op_sel:[1,0]
	v_pk_fma_f32 v[28:29], v[36:37], v[66:67], v[28:29] op_sel:[0,1,0]
	v_pk_mul_f32 v[30:31], v[70:71], v[30:31] op_sel:[1,0]
	v_pk_fma_f32 v[36:37], v[38:39], v[66:67], v[18:19] op_sel:[0,1,0]
	v_add_co_u32_e32 v38, vcc, s7, v86
	v_pk_fma_f32 v[30:31], v[40:41], v[66:67], v[30:31] op_sel:[0,1,0]
	v_cvt_pk_bf16_f32 v18, v26, v27
	v_cvt_pk_bf16_f32 v19, v22, v23
	v_cvt_pk_bf16_f32 v20, v28, v29
	v_cvt_pk_bf16_f32 v21, v24, v25
	v_addc_co_u32_e32 v39, vcc, 0, v87, vcc
	global_store_dwordx4 v[38:39], v[18:21], off
	s_mov_b32 s7, 0x27c60000
	s_nop 0
	v_cvt_pk_bf16_f32 v18, v30, v31
	v_cvt_pk_bf16_f32 v19, v32, v33
	v_cvt_pk_bf16_f32 v20, v34, v35
	v_cvt_pk_bf16_f32 v21, v36, v37
	global_store_dwordx4 v[38:39], v[18:21], off offset:512
	s_waitcnt vmcnt(60)
	s_nop 0
	v_lshlrev_b32_e32 v18, 16, v14
	v_and_b32_e32 v19, 0xffff0000, v14
	v_lshlrev_b32_e32 v14, 16, v15
	v_and_b32_e32 v15, 0xffff0000, v15
	v_pk_mul_f32 v[14:15], v[72:73], v[14:15] op_sel_hi:[0,1]
	v_pk_fma_f32 v[14:15], v[22:23], v[68:69], v[14:15] op_sel_hi:[1,0,1]
	v_lshlrev_b32_e32 v20, 16, v16
	v_and_b32_e32 v21, 0xffff0000, v16
	v_lshlrev_b32_e32 v16, 16, v17
	v_and_b32_e32 v17, 0xffff0000, v17
	s_waitcnt vmcnt(59)
	v_lshlrev_b32_e32 v22, 16, v10
	v_and_b32_e32 v23, 0xffff0000, v10
	v_lshlrev_b32_e32 v10, 16, v11
	v_and_b32_e32 v11, 0xffff0000, v11
	v_pk_mul_f32 v[16:17], v[72:73], v[16:17] op_sel_hi:[0,1]
	v_pk_mul_f32 v[10:11], v[72:73], v[10:11] op_sel_hi:[0,1]
	v_pk_fma_f32 v[16:17], v[24:25], v[68:69], v[16:17] op_sel_hi:[1,0,1]
	v_pk_fma_f32 v[24:25], v[32:33], v[68:69], v[10:11] op_sel_hi:[1,0,1]
	v_lshlrev_b32_e32 v10, 16, v12
	v_and_b32_e32 v11, 0xffff0000, v12
	v_pk_mul_f32 v[18:19], v[72:73], v[18:19] op_sel_hi:[0,1]
	v_pk_mul_f32 v[10:11], v[72:73], v[10:11] op_sel_hi:[0,1]
	v_pk_fma_f32 v[18:19], v[26:27], v[68:69], v[18:19] op_sel_hi:[1,0,1]
	v_pk_mul_f32 v[20:21], v[72:73], v[20:21] op_sel_hi:[0,1]
	v_pk_mul_f32 v[22:23], v[72:73], v[22:23] op_sel_hi:[0,1]
	v_pk_fma_f32 v[26:27], v[34:35], v[68:69], v[10:11] op_sel_hi:[1,0,1]
	v_lshlrev_b32_e32 v10, 16, v13
	v_and_b32_e32 v11, 0xffff0000, v13
	v_pk_fma_f32 v[20:21], v[28:29], v[68:69], v[20:21] op_sel_hi:[1,0,1]
	v_pk_fma_f32 v[22:23], v[30:31], v[68:69], v[22:23] op_sel_hi:[1,0,1]
	v_pk_mul_f32 v[10:11], v[72:73], v[10:11] op_sel_hi:[0,1]
	v_add_co_u32_e32 v30, vcc, s7, v86
	v_pk_fma_f32 v[28:29], v[36:37], v[68:69], v[10:11] op_sel_hi:[1,0,1]
	v_cvt_pk_bf16_f32 v10, v18, v19
	v_cvt_pk_bf16_f32 v11, v14, v15
	v_cvt_pk_bf16_f32 v12, v20, v21
	v_cvt_pk_bf16_f32 v13, v16, v17
	v_addc_co_u32_e32 v31, vcc, 0, v87, vcc
	global_store_dwordx4 v[30:31], v[10:13], off
	s_mov_b32 s7, 0x27c80000
	s_nop 0
	v_cvt_pk_bf16_f32 v10, v22, v23
	v_cvt_pk_bf16_f32 v11, v24, v25
	v_cvt_pk_bf16_f32 v12, v26, v27
	v_cvt_pk_bf16_f32 v13, v28, v29
	global_store_dwordx4 v[30:31], v[10:13], off offset:512
	s_waitcnt vmcnt(60)
	s_nop 0
	v_lshlrev_b32_e32 v12, 16, v6
	v_and_b32_e32 v13, 0xffff0000, v6
	v_mov_b32_e32 v6, v73
	v_mov_b32_e32 v10, v69
	v_pk_mul_f32 v[12:13], v[6:7], v[12:13] op_sel_hi:[0,1]
	v_pk_fma_f32 v[90:91], v[18:19], v[10:11], v[12:13] op_sel_hi:[1,0,1]
	v_lshlrev_b32_e32 v12, 16, v7
	v_and_b32_e32 v13, 0xffff0000, v7
	v_pk_mul_f32 v[12:13], v[6:7], v[12:13] op_sel_hi:[0,1]
	v_pk_fma_f32 v[92:93], v[14:15], v[10:11], v[12:13] op_sel_hi:[1,0,1]
	v_lshlrev_b32_e32 v12, 16, v8
	v_and_b32_e32 v13, 0xffff0000, v8
	v_lshlrev_b32_e32 v8, 16, v9
	v_and_b32_e32 v9, 0xffff0000, v9
	v_pk_mul_f32 v[8:9], v[6:7], v[8:9] op_sel_hi:[0,1]
	v_pk_fma_f32 v[96:97], v[16:17], v[10:11], v[8:9] op_sel_hi:[1,0,1]
	s_waitcnt vmcnt(59)
	v_lshlrev_b32_e32 v8, 16, v2
	v_and_b32_e32 v9, 0xffff0000, v2
	v_lshlrev_b32_e32 v2, 16, v3
	v_and_b32_e32 v3, 0xffff0000, v3
	v_pk_mul_f32 v[2:3], v[6:7], v[2:3] op_sel_hi:[0,1]
	v_pk_fma_f32 v[100:101], v[24:25], v[10:11], v[2:3] op_sel_hi:[1,0,1]
	v_lshlrev_b32_e32 v2, 16, v4
	v_and_b32_e32 v3, 0xffff0000, v4
	v_pk_mul_f32 v[2:3], v[6:7], v[2:3] op_sel_hi:[0,1]
	v_pk_mul_f32 v[12:13], v[6:7], v[12:13] op_sel_hi:[0,1]
	v_pk_fma_f32 v[102:103], v[26:27], v[10:11], v[2:3] op_sel_hi:[1,0,1]
	v_lshlrev_b32_e32 v2, 16, v5
	v_and_b32_e32 v3, 0xffff0000, v5
	v_pk_fma_f32 v[94:95], v[20:21], v[10:11], v[12:13] op_sel_hi:[1,0,1]
	v_pk_mul_f32 v[8:9], v[6:7], v[8:9] op_sel_hi:[0,1]
	v_pk_mul_f32 v[2:3], v[6:7], v[2:3] op_sel_hi:[0,1]
	v_add_co_u32_e32 v6, vcc, s7, v86
	v_pk_fma_f32 v[98:99], v[22:23], v[10:11], v[8:9] op_sel_hi:[1,0,1]
	v_pk_fma_f32 v[104:105], v[28:29], v[10:11], v[2:3] op_sel_hi:[1,0,1]
	v_cvt_pk_bf16_f32 v2, v90, v91
	v_cvt_pk_bf16_f32 v3, v92, v93
	v_cvt_pk_bf16_f32 v4, v94, v95
	v_cvt_pk_bf16_f32 v5, v96, v97
	v_addc_co_u32_e32 v7, vcc, 0, v87, vcc
	global_store_dwordx4 v[6:7], v[2:5], off
	s_mov_b32 s7, 0x23c80000
	s_nop 0
	v_cvt_pk_bf16_f32 v2, v98, v99
	v_cvt_pk_bf16_f32 v3, v100, v101
	v_cvt_pk_bf16_f32 v4, v102, v103
	v_cvt_pk_bf16_f32 v5, v104, v105
	global_store_dwordx4 v[6:7], v[2:5], off offset:512
	s_nop 1
	v_add_co_u32_e32 v2, vcc, s7, v88
	s_mov_b32 s7, 0
	s_nop 0
	v_addc_co_u32_e32 v3, vcc, 0, v89, vcc
	s_waitcnt vmcnt(16)
	v_mov_b32_e32 v78, v110
	v_mov_b32_e32 v79, v111
	v_mov_b32_e32 v80, v112
	v_mov_b32_e32 v81, v113
	v_lshl_add_u64 v[2:3], v[88:89], 0, s[8:9]
	v_mov_b32_e32 v74, v114
	v_mov_b32_e32 v75, v115
	v_mov_b32_e32 v76, v116
	v_mov_b32_e32 v77, v117
	s_mov_b64 s[8:9], 0x23ca0000
	v_lshl_add_u64 v[2:3], v[88:89], 0, s[8:9]
	s_mov_b32 s8, 0x23ca0000
	v_add_co_u32_e32 v4, vcc, s8, v88
	s_mov_b64 s[8:9], 0x23cc0000
	s_nop 0
	v_addc_co_u32_e32 v5, vcc, 0, v89, vcc
	v_mov_b32_e32 v70, v118
	v_mov_b32_e32 v71, v119
	v_mov_b32_e32 v72, v120
	v_mov_b32_e32 v73, v121
	v_mov_b32_e32 v58, v122
	v_mov_b32_e32 v59, v123
	v_mov_b32_e32 v60, v124
	v_mov_b32_e32 v61, v125
	v_lshl_add_u64 v[2:3], v[88:89], 0, s[8:9]
	s_mov_b32 s8, 0x23cc0000
	v_add_co_u32_e32 v4, vcc, s8, v88
	s_mov_b64 s[8:9], 0x23ce0000
	s_nop 0
	v_addc_co_u32_e32 v5, vcc, 0, v89, vcc
	v_mov_b32_e32 v54, v126
	v_mov_b32_e32 v55, v127
	v_mov_b32_e32 v56, v128
	v_mov_b32_e32 v57, v129
	v_mov_b32_e32 v42, v130
	v_mov_b32_e32 v43, v131
	v_mov_b32_e32 v44, v132
	v_mov_b32_e32 v45, v133
	v_lshl_add_u64 v[2:3], v[88:89], 0, s[8:9]
	s_mov_b32 s8, 0x23ce0000
	v_add_co_u32_e32 v4, vcc, s8, v88
	s_mov_b64 s[8:9], 0x23d00000
	s_nop 0
	v_addc_co_u32_e32 v5, vcc, 0, v89, vcc
	v_mov_b32_e32 v38, v134
	v_mov_b32_e32 v39, v135
	v_mov_b32_e32 v40, v136
	v_mov_b32_e32 v41, v137
	v_mov_b32_e32 v34, v138
	v_mov_b32_e32 v35, v139
	v_mov_b32_e32 v36, v140
	v_mov_b32_e32 v37, v141
	v_lshl_add_u64 v[2:3], v[88:89], 0, s[8:9]
	s_mov_b32 s8, 0x23d00000
	v_add_co_u32_e32 v4, vcc, s8, v88
	s_mov_b64 s[8:9], 0x23d20000
	s_nop 0
	v_addc_co_u32_e32 v5, vcc, 0, v89, vcc
	v_mov_b32_e32 v30, v142
	v_mov_b32_e32 v31, v143
	v_mov_b32_e32 v32, v144
	v_mov_b32_e32 v33, v145
	v_mov_b32_e32 v26, v146
	v_mov_b32_e32 v27, v147
	v_mov_b32_e32 v28, v148
	v_mov_b32_e32 v29, v149
	v_lshl_add_u64 v[2:3], v[88:89], 0, s[8:9]
	s_mov_b32 s8, 0x23d20000
	v_add_co_u32_e32 v4, vcc, s8, v88
	s_mov_b64 s[8:9], 0x23d40000
	s_nop 0
	v_addc_co_u32_e32 v5, vcc, 0, v89, vcc
	v_mov_b32_e32 v22, v150
	v_mov_b32_e32 v23, v151
	v_mov_b32_e32 v24, v152
	v_mov_b32_e32 v25, v153
	v_mov_b32_e32 v18, v154
	v_mov_b32_e32 v19, v155
	v_mov_b32_e32 v20, v156
	v_mov_b32_e32 v21, v157
	v_lshl_add_u64 v[2:3], v[88:89], 0, s[8:9]
	s_mov_b32 s8, 0x23d40000
	v_add_co_u32_e32 v4, vcc, s8, v88
	s_mov_b64 s[8:9], 0x23d60000
	s_nop 0
	v_addc_co_u32_e32 v5, vcc, 0, v89, vcc
	v_mov_b32_e32 v14, v158
	v_mov_b32_e32 v15, v159
	v_mov_b32_e32 v16, v160
	v_mov_b32_e32 v17, v161
	v_mov_b32_e32 v10, v162
	v_mov_b32_e32 v11, v163
	v_mov_b32_e32 v12, v164
	v_mov_b32_e32 v13, v165
	v_lshl_add_u64 v[46:47], v[88:89], 0, s[8:9]
	s_mov_b32 s8, 0x23d60000
	v_add_co_u32_e32 v48, vcc, s8, v88
	s_mov_b32 s8, 0x27ca0000
	s_nop 0
	v_addc_co_u32_e32 v49, vcc, 0, v89, vcc
	v_mov_b32_e32 v6, v166
	v_mov_b32_e32 v7, v167
	v_mov_b32_e32 v8, v168
	v_mov_b32_e32 v9, v169
	v_mov_b32_e32 v2, v170
	v_mov_b32_e32 v3, v171
	v_mov_b32_e32 v4, v172
	v_mov_b32_e32 v5, v173
	ds_read_b128 v[62:65], v83 offset:96
	ds_read_b128 v[66:69], v83 offset:32
	ds_read_b128 v[50:53], v83 offset:112
	v_lshlrev_b32_e32 v46, 16, v78
	v_and_b32_e32 v47, 0xffff0000, v78
	v_lshlrev_b32_e32 v78, 16, v79
	v_and_b32_e32 v79, 0xffff0000, v79
	s_waitcnt lgkmcnt(2)
	v_pk_mul_f32 v[88:89], v[62:63], v[46:47] op_sel_hi:[0,1]
	v_pk_mul_f32 v[78:79], v[62:63], v[78:79] op_sel_hi:[0,1]
	s_waitcnt lgkmcnt(1)
	v_pk_fma_f32 v[88:89], v[90:91], v[66:67], v[88:89] op_sel_hi:[1,0,1]
	v_pk_fma_f32 v[78:79], v[92:93], v[66:67], v[78:79] op_sel_hi:[1,0,1]
	v_lshlrev_b32_e32 v90, 16, v80
	v_and_b32_e32 v91, 0xffff0000, v80
	v_lshlrev_b32_e32 v92, 16, v74
	v_and_b32_e32 v93, 0xffff0000, v74
	v_lshlrev_b32_e32 v74, 16, v75
	v_and_b32_e32 v75, 0xffff0000, v75
	v_pk_mul_f32 v[90:91], v[62:63], v[90:91] op_sel_hi:[0,1]
	v_pk_mul_f32 v[74:75], v[62:63], v[74:75] op_sel_hi:[0,1]
	v_pk_fma_f32 v[90:91], v[94:95], v[66:67], v[90:91] op_sel_hi:[1,0,1]
	v_lshlrev_b32_e32 v80, 16, v81
	v_and_b32_e32 v81, 0xffff0000, v81
	v_pk_fma_f32 v[94:95], v[100:101], v[66:67], v[74:75] op_sel_hi:[1,0,1]
	v_lshlrev_b32_e32 v74, 16, v76
	v_and_b32_e32 v75, 0xffff0000, v76
	v_pk_mul_f32 v[80:81], v[62:63], v[80:81] op_sel_hi:[0,1]
	v_pk_mul_f32 v[74:75], v[62:63], v[74:75] op_sel_hi:[0,1]
	v_pk_fma_f32 v[80:81], v[96:97], v[66:67], v[80:81] op_sel_hi:[1,0,1]
	v_pk_fma_f32 v[96:97], v[102:103], v[66:67], v[74:75] op_sel_hi:[1,0,1]
	v_lshlrev_b32_e32 v74, 16, v77
	v_and_b32_e32 v75, 0xffff0000, v77
	v_pk_mul_f32 v[92:93], v[62:63], v[92:93] op_sel_hi:[0,1]
	v_pk_mul_f32 v[74:75], v[62:63], v[74:75] op_sel_hi:[0,1]
	v_add_co_u32_e32 v100, vcc, s8, v86
	v_pk_fma_f32 v[92:93], v[98:99], v[66:67], v[92:93] op_sel_hi:[1,0,1]
	v_pk_fma_f32 v[98:99], v[104:105], v[66:67], v[74:75] op_sel_hi:[1,0,1]
	v_cvt_pk_bf16_f32 v74, v88, v89
	v_cvt_pk_bf16_f32 v75, v78, v79
	v_cvt_pk_bf16_f32 v76, v90, v91
	v_cvt_pk_bf16_f32 v77, v80, v81
	v_addc_co_u32_e32 v101, vcc, 0, v87, vcc
	global_store_dwordx4 v[100:101], v[74:77], off
	s_mov_b32 s8, 0x27cc0000
	ds_read_b128 v[46:49], v83 offset:48
	v_cvt_pk_bf16_f32 v74, v92, v93
	v_cvt_pk_bf16_f32 v75, v94, v95
	v_cvt_pk_bf16_f32 v76, v96, v97
	v_cvt_pk_bf16_f32 v77, v98, v99
	global_store_dwordx4 v[100:101], v[74:77], off offset:512
	s_nop 0
	v_lshlrev_b32_e32 v74, 16, v70
	v_and_b32_e32 v75, 0xffff0000, v70
	v_lshlrev_b32_e32 v70, 16, v71
	v_and_b32_e32 v71, 0xffff0000, v71
	v_pk_mul_f32 v[70:71], v[62:63], v[70:71] op_sel:[1,0]
	v_lshlrev_b32_e32 v76, 16, v72
	v_pk_fma_f32 v[70:71], v[78:79], v[66:67], v[70:71] op_sel:[0,1,0]
	v_and_b32_e32 v77, 0xffff0000, v72
	v_lshlrev_b32_e32 v72, 16, v73
	v_and_b32_e32 v73, 0xffff0000, v73
	v_lshlrev_b32_e32 v78, 16, v58
	v_and_b32_e32 v79, 0xffff0000, v58
	v_lshlrev_b32_e32 v58, 16, v59
	v_and_b32_e32 v59, 0xffff0000, v59
	v_pk_mul_f32 v[72:73], v[62:63], v[72:73] op_sel:[1,0]
	v_pk_mul_f32 v[58:59], v[62:63], v[58:59] op_sel:[1,0]
	v_pk_fma_f32 v[72:73], v[80:81], v[66:67], v[72:73] op_sel:[0,1,0]
	v_pk_fma_f32 v[80:81], v[94:95], v[66:67], v[58:59] op_sel:[0,1,0]
	v_lshlrev_b32_e32 v58, 16, v60
	v_and_b32_e32 v59, 0xffff0000, v60
	v_pk_mul_f32 v[74:75], v[62:63], v[74:75] op_sel:[1,0]
	v_pk_mul_f32 v[58:59], v[62:63], v[58:59] op_sel:[1,0]
	v_pk_fma_f32 v[74:75], v[88:89], v[66:67], v[74:75] op_sel:[0,1,0]
	v_pk_fma_f32 v[88:89], v[96:97], v[66:67], v[58:59] op_sel:[0,1,0]
	v_lshlrev_b32_e32 v58, 16, v61
	v_and_b32_e32 v59, 0xffff0000, v61
	v_pk_mul_f32 v[76:77], v[62:63], v[76:77] op_sel:[1,0]
	v_pk_mul_f32 v[78:79], v[62:63], v[78:79] op_sel:[1,0]
	v_pk_mul_f32 v[58:59], v[62:63], v[58:59] op_sel:[1,0]
	v_pk_fma_f32 v[76:77], v[90:91], v[66:67], v[76:77] op_sel:[0,1,0]
	v_pk_fma_f32 v[78:79], v[92:93], v[66:67], v[78:79] op_sel:[0,1,0]
	v_pk_fma_f32 v[62:63], v[98:99], v[66:67], v[58:59] op_sel:[0,1,0]
	v_add_co_u32_e32 v66, vcc, s8, v86
	v_cvt_pk_bf16_f32 v58, v74, v75
	v_cvt_pk_bf16_f32 v59, v70, v71
	v_cvt_pk_bf16_f32 v60, v76, v77
	v_cvt_pk_bf16_f32 v61, v72, v73
	v_addc_co_u32_e32 v67, vcc, 0, v87, vcc
	global_store_dwordx4 v[66:67], v[58:61], off
	s_mov_b32 s8, 0x27ce0000
	s_nop 0
	v_cvt_pk_bf16_f32 v58, v78, v79
	v_cvt_pk_bf16_f32 v59, v80, v81
	v_cvt_pk_bf16_f32 v60, v88, v89
	v_cvt_pk_bf16_f32 v61, v62, v63
	global_store_dwordx4 v[66:67], v[58:61], off offset:512
	v_lshlrev_b32_e32 v66, 16, v42
	v_and_b32_e32 v67, 0xffff0000, v42
	v_lshlrev_b32_e32 v58, 16, v54
	v_and_b32_e32 v59, 0xffff0000, v54
	v_lshlrev_b32_e32 v54, 16, v55
	v_and_b32_e32 v55, 0xffff0000, v55
	v_lshlrev_b32_e32 v42, 16, v43
	v_and_b32_e32 v43, 0xffff0000, v43
	v_pk_mul_f32 v[54:55], v[64:65], v[54:55] op_sel_hi:[0,1]
	v_pk_mul_f32 v[42:43], v[64:65], v[42:43] op_sel_hi:[0,1]
	v_pk_fma_f32 v[54:55], v[70:71], v[68:69], v[54:55] op_sel_hi:[1,0,1]
	v_lshlrev_b32_e32 v60, 16, v56
	v_and_b32_e32 v61, 0xffff0000, v56
	v_lshlrev_b32_e32 v56, 16, v57
	v_and_b32_e32 v57, 0xffff0000, v57
	v_pk_fma_f32 v[70:71], v[80:81], v[68:69], v[42:43] op_sel_hi:[1,0,1]
	v_lshlrev_b32_e32 v42, 16, v44
	v_and_b32_e32 v43, 0xffff0000, v44
	v_pk_mul_f32 v[56:57], v[64:65], v[56:57] op_sel_hi:[0,1]
	v_pk_mul_f32 v[42:43], v[64:65], v[42:43] op_sel_hi:[0,1]
	v_pk_mul_f32 v[58:59], v[64:65], v[58:59] op_sel_hi:[0,1]
	v_pk_mul_f32 v[60:61], v[64:65], v[60:61] op_sel_hi:[0,1]
	v_pk_fma_f32 v[56:57], v[72:73], v[68:69], v[56:57] op_sel_hi:[1,0,1]
	v_pk_fma_f32 v[72:73], v[88:89], v[68:69], v[42:43] op_sel_hi:[1,0,1]
	v_lshlrev_b32_e32 v42, 16, v45
	v_and_b32_e32 v43, 0xffff0000, v45
	v_pk_fma_f32 v[58:59], v[74:75], v[68:69], v[58:59] op_sel_hi:[1,0,1]
	v_pk_fma_f32 v[60:61], v[76:77], v[68:69], v[60:61] op_sel_hi:[1,0,1]
	v_pk_mul_f32 v[66:67], v[64:65], v[66:67] op_sel_hi:[0,1]
	v_pk_mul_f32 v[42:43], v[64:65], v[42:43] op_sel_hi:[0,1]
	v_add_co_u32_e32 v74, vcc, s8, v86
	v_pk_fma_f32 v[66:67], v[78:79], v[68:69], v[66:67] op_sel_hi:[1,0,1]
	v_pk_fma_f32 v[62:63], v[62:63], v[68:69], v[42:43] op_sel_hi:[1,0,1]
	v_cvt_pk_bf16_f32 v42, v58, v59
	v_cvt_pk_bf16_f32 v43, v54, v55
	v_cvt_pk_bf16_f32 v44, v60, v61
	v_cvt_pk_bf16_f32 v45, v56, v57
	v_addc_co_u32_e32 v75, vcc, 0, v87, vcc
	global_store_dwordx4 v[74:75], v[42:45], off
	s_mov_b32 s8, 0x27d00000
	s_nop 0
	v_cvt_pk_bf16_f32 v42, v66, v67
	v_cvt_pk_bf16_f32 v43, v70, v71
	v_cvt_pk_bf16_f32 v44, v72, v73
	v_cvt_pk_bf16_f32 v45, v62, v63
	global_store_dwordx4 v[74:75], v[42:45], off offset:512
	s_nop 0
	v_lshlrev_b32_e32 v44, 16, v38
	v_and_b32_e32 v45, 0xffff0000, v38
	v_mov_b32_e32 v38, v65
	v_mov_b32_e32 v42, v69
	v_pk_mul_f32 v[44:45], v[38:39], v[44:45] op_sel_hi:[0,1]
	v_pk_fma_f32 v[44:45], v[58:59], v[42:43], v[44:45] op_sel_hi:[1,0,1]
	v_lshlrev_b32_e32 v58, 16, v39
	v_and_b32_e32 v59, 0xffff0000, v39
	v_pk_mul_f32 v[58:59], v[38:39], v[58:59] op_sel_hi:[0,1]
	v_pk_fma_f32 v[54:55], v[54:55], v[42:43], v[58:59] op_sel_hi:[1,0,1]
	v_lshlrev_b32_e32 v58, 16, v40
	v_and_b32_e32 v59, 0xffff0000, v40
	v_lshlrev_b32_e32 v40, 16, v41
	v_and_b32_e32 v41, 0xffff0000, v41
	v_pk_mul_f32 v[40:41], v[38:39], v[40:41] op_sel_hi:[0,1]
	v_pk_fma_f32 v[40:41], v[56:57], v[42:43], v[40:41] op_sel_hi:[1,0,1]
	v_lshlrev_b32_e32 v56, 16, v34
	v_and_b32_e32 v57, 0xffff0000, v34
	v_lshlrev_b32_e32 v34, 16, v35
	v_and_b32_e32 v35, 0xffff0000, v35
	v_pk_mul_f32 v[58:59], v[38:39], v[58:59] op_sel_hi:[0,1]
	v_pk_mul_f32 v[34:35], v[38:39], v[34:35] op_sel_hi:[0,1]
	v_pk_fma_f32 v[58:59], v[60:61], v[42:43], v[58:59] op_sel_hi:[1,0,1]
	v_pk_fma_f32 v[60:61], v[70:71], v[42:43], v[34:35] op_sel_hi:[1,0,1]
	v_lshlrev_b32_e32 v34, 16, v36
	v_and_b32_e32 v35, 0xffff0000, v36
	v_pk_mul_f32 v[34:35], v[38:39], v[34:35] op_sel_hi:[0,1]
	v_pk_fma_f32 v[64:65], v[72:73], v[42:43], v[34:35] op_sel_hi:[1,0,1]
	v_lshlrev_b32_e32 v34, 16, v37
	v_and_b32_e32 v35, 0xffff0000, v37
	v_pk_mul_f32 v[56:57], v[38:39], v[56:57] op_sel_hi:[0,1]
	v_pk_mul_f32 v[34:35], v[38:39], v[34:35] op_sel_hi:[0,1]
	v_pk_fma_f32 v[56:57], v[66:67], v[42:43], v[56:57] op_sel_hi:[1,0,1]
	v_pk_fma_f32 v[38:39], v[62:63], v[42:43], v[34:35] op_sel_hi:[1,0,1]
	v_add_co_u32_e32 v42, vcc, s8, v86
	v_cvt_pk_bf16_f32 v34, v44, v45
	v_cvt_pk_bf16_f32 v35, v54, v55
	v_cvt_pk_bf16_f32 v36, v58, v59
	v_cvt_pk_bf16_f32 v37, v40, v41
	v_addc_co_u32_e32 v43, vcc, 0, v87, vcc
	global_store_dwordx4 v[42:43], v[34:37], off
	s_mov_b32 s8, 0x27d20000
	s_nop 0
	v_cvt_pk_bf16_f32 v34, v56, v57
	v_cvt_pk_bf16_f32 v35, v60, v61
	v_cvt_pk_bf16_f32 v36, v64, v65
	v_cvt_pk_bf16_f32 v37, v38, v39
	global_store_dwordx4 v[42:43], v[34:37], off offset:512
	s_nop 0
	v_lshlrev_b32_e32 v36, 16, v32
	v_and_b32_e32 v37, 0xffff0000, v32
	v_lshlrev_b32_e32 v32, 16, v33
	v_and_b32_e32 v33, 0xffff0000, v33
	s_waitcnt lgkmcnt(1)
	v_pk_mul_f32 v[32:33], v[50:51], v[32:33] op_sel_hi:[0,1]
	s_waitcnt lgkmcnt(0)
	v_pk_fma_f32 v[32:33], v[40:41], v[46:47], v[32:33] op_sel_hi:[1,0,1]
	v_lshlrev_b32_e32 v40, 16, v26
	v_and_b32_e32 v41, 0xffff0000, v26
	v_lshlrev_b32_e32 v26, 16, v27
	v_and_b32_e32 v27, 0xffff0000, v27
	v_pk_mul_f32 v[26:27], v[50:51], v[26:27] op_sel_hi:[0,1]
	v_lshlrev_b32_e32 v34, 16, v30
	v_and_b32_e32 v35, 0xffff0000, v30
	v_pk_fma_f32 v[42:43], v[60:61], v[46:47], v[26:27] op_sel_hi:[1,0,1]
	v_lshlrev_b32_e32 v26, 16, v28
	v_and_b32_e32 v27, 0xffff0000, v28
	v_pk_mul_f32 v[34:35], v[50:51], v[34:35] op_sel_hi:[0,1]
	v_lshlrev_b32_e32 v30, 16, v31
	v_and_b32_e32 v31, 0xffff0000, v31
	v_pk_mul_f32 v[26:27], v[50:51], v[26:27] op_sel_hi:[0,1]
	v_pk_fma_f32 v[34:35], v[44:45], v[46:47], v[34:35] op_sel_hi:[1,0,1]
	v_pk_mul_f32 v[30:31], v[50:51], v[30:31] op_sel_hi:[0,1]
	v_pk_mul_f32 v[36:37], v[50:51], v[36:37] op_sel_hi:[0,1]
	v_pk_fma_f32 v[44:45], v[64:65], v[46:47], v[26:27] op_sel_hi:[1,0,1]
	v_lshlrev_b32_e32 v26, 16, v29
	v_and_b32_e32 v27, 0xffff0000, v29
	v_pk_fma_f32 v[30:31], v[54:55], v[46:47], v[30:31] op_sel_hi:[1,0,1]
	v_pk_fma_f32 v[36:37], v[58:59], v[46:47], v[36:37] op_sel_hi:[1,0,1]
	v_pk_mul_f32 v[40:41], v[50:51], v[40:41] op_sel_hi:[0,1]
	v_pk_mul_f32 v[26:27], v[50:51], v[26:27] op_sel_hi:[0,1]
	v_add_co_u32_e32 v54, vcc, s8, v86
	v_pk_fma_f32 v[40:41], v[56:57], v[46:47], v[40:41] op_sel_hi:[1,0,1]
	v_pk_fma_f32 v[38:39], v[38:39], v[46:47], v[26:27] op_sel_hi:[1,0,1]
	v_cvt_pk_bf16_f32 v26, v34, v35
	v_cvt_pk_bf16_f32 v27, v30, v31
	v_cvt_pk_bf16_f32 v28, v36, v37
	v_cvt_pk_bf16_f32 v29, v32, v33
	v_addc_co_u32_e32 v55, vcc, 0, v87, vcc
	global_store_dwordx4 v[54:55], v[26:29], off
	s_mov_b32 s8, 0x27d40000
	s_nop 0
	v_cvt_pk_bf16_f32 v26, v40, v41
	v_cvt_pk_bf16_f32 v27, v42, v43
	v_cvt_pk_bf16_f32 v28, v44, v45
	v_cvt_pk_bf16_f32 v29, v38, v39
	global_store_dwordx4 v[54:55], v[26:29], off offset:512
	s_nop 0
	v_lshlrev_b32_e32 v26, 16, v22
	v_and_b32_e32 v27, 0xffff0000, v22
	v_lshlrev_b32_e32 v22, 16, v23
	v_and_b32_e32 v23, 0xffff0000, v23
	v_pk_mul_f32 v[22:23], v[50:51], v[22:23] op_sel:[1,0]
	v_lshlrev_b32_e32 v28, 16, v24
	v_pk_fma_f32 v[22:23], v[30:31], v[46:47], v[22:23] op_sel:[0,1,0]
	v_and_b32_e32 v29, 0xffff0000, v24
	v_lshlrev_b32_e32 v24, 16, v25
	v_and_b32_e32 v25, 0xffff0000, v25
	v_lshlrev_b32_e32 v30, 16, v18
	v_and_b32_e32 v31, 0xffff0000, v18
	v_lshlrev_b32_e32 v18, 16, v19
	v_and_b32_e32 v19, 0xffff0000, v19
	v_pk_mul_f32 v[24:25], v[50:51], v[24:25] op_sel:[1,0]
	v_pk_mul_f32 v[18:19], v[50:51], v[18:19] op_sel:[1,0]
	v_pk_fma_f32 v[24:25], v[32:33], v[46:47], v[24:25] op_sel:[0,1,0]
	v_pk_fma_f32 v[32:33], v[42:43], v[46:47], v[18:19] op_sel:[0,1,0]
	v_lshlrev_b32_e32 v18, 16, v20
	v_and_b32_e32 v19, 0xffff0000, v20
	v_pk_mul_f32 v[26:27], v[50:51], v[26:27] op_sel:[1,0]
	v_pk_mul_f32 v[18:19], v[50:51], v[18:19] op_sel:[1,0]
	v_pk_fma_f32 v[26:27], v[34:35], v[46:47], v[26:27] op_sel:[0,1,0]
	v_pk_fma_f32 v[34:35], v[44:45], v[46:47], v[18:19] op_sel:[0,1,0]
	v_lshlrev_b32_e32 v18, 16, v21
	v_and_b32_e32 v19, 0xffff0000, v21
	v_pk_mul_f32 v[28:29], v[50:51], v[28:29] op_sel:[1,0]
	v_pk_mul_f32 v[18:19], v[50:51], v[18:19] op_sel:[1,0]
	v_pk_fma_f32 v[28:29], v[36:37], v[46:47], v[28:29] op_sel:[0,1,0]
	v_pk_mul_f32 v[30:31], v[50:51], v[30:31] op_sel:[1,0]
	v_pk_fma_f32 v[36:37], v[38:39], v[46:47], v[18:19] op_sel:[0,1,0]
	v_add_co_u32_e32 v38, vcc, s8, v86
	v_pk_fma_f32 v[30:31], v[40:41], v[46:47], v[30:31] op_sel:[0,1,0]
	v_cvt_pk_bf16_f32 v18, v26, v27
	v_cvt_pk_bf16_f32 v19, v22, v23
	v_cvt_pk_bf16_f32 v20, v28, v29
	v_cvt_pk_bf16_f32 v21, v24, v25
	v_addc_co_u32_e32 v39, vcc, 0, v87, vcc
	global_store_dwordx4 v[38:39], v[18:21], off
	s_mov_b32 s8, 0x27d60000
	s_nop 0
	v_cvt_pk_bf16_f32 v18, v30, v31
	v_cvt_pk_bf16_f32 v19, v32, v33
	v_cvt_pk_bf16_f32 v20, v34, v35
	v_cvt_pk_bf16_f32 v21, v36, v37
	global_store_dwordx4 v[38:39], v[18:21], off offset:512
	s_nop 0
	v_lshlrev_b32_e32 v18, 16, v14
	v_and_b32_e32 v19, 0xffff0000, v14
	v_lshlrev_b32_e32 v14, 16, v15
	v_and_b32_e32 v15, 0xffff0000, v15
	v_pk_mul_f32 v[14:15], v[52:53], v[14:15] op_sel_hi:[0,1]
	v_pk_fma_f32 v[14:15], v[22:23], v[48:49], v[14:15] op_sel_hi:[1,0,1]
	v_lshlrev_b32_e32 v20, 16, v16
	v_and_b32_e32 v21, 0xffff0000, v16
	v_lshlrev_b32_e32 v16, 16, v17
	v_and_b32_e32 v17, 0xffff0000, v17
	v_lshlrev_b32_e32 v22, 16, v10
	v_and_b32_e32 v23, 0xffff0000, v10
	v_lshlrev_b32_e32 v10, 16, v11
	v_and_b32_e32 v11, 0xffff0000, v11
	v_pk_mul_f32 v[16:17], v[52:53], v[16:17] op_sel_hi:[0,1]
	v_pk_mul_f32 v[10:11], v[52:53], v[10:11] op_sel_hi:[0,1]
	v_pk_fma_f32 v[16:17], v[24:25], v[48:49], v[16:17] op_sel_hi:[1,0,1]
	v_pk_fma_f32 v[24:25], v[32:33], v[48:49], v[10:11] op_sel_hi:[1,0,1]
	v_lshlrev_b32_e32 v10, 16, v12
	v_and_b32_e32 v11, 0xffff0000, v12
	v_pk_mul_f32 v[18:19], v[52:53], v[18:19] op_sel_hi:[0,1]
	v_pk_mul_f32 v[10:11], v[52:53], v[10:11] op_sel_hi:[0,1]
	v_pk_fma_f32 v[18:19], v[26:27], v[48:49], v[18:19] op_sel_hi:[1,0,1]
	v_pk_mul_f32 v[20:21], v[52:53], v[20:21] op_sel_hi:[0,1]
	v_pk_mul_f32 v[22:23], v[52:53], v[22:23] op_sel_hi:[0,1]
	v_pk_fma_f32 v[26:27], v[34:35], v[48:49], v[10:11] op_sel_hi:[1,0,1]
	v_lshlrev_b32_e32 v10, 16, v13
	v_and_b32_e32 v11, 0xffff0000, v13
	v_pk_fma_f32 v[20:21], v[28:29], v[48:49], v[20:21] op_sel_hi:[1,0,1]
	v_pk_fma_f32 v[22:23], v[30:31], v[48:49], v[22:23] op_sel_hi:[1,0,1]
	v_pk_mul_f32 v[10:11], v[52:53], v[10:11] op_sel_hi:[0,1]
	v_add_co_u32_e32 v30, vcc, s8, v86
	v_pk_fma_f32 v[28:29], v[36:37], v[48:49], v[10:11] op_sel_hi:[1,0,1]
	v_cvt_pk_bf16_f32 v10, v18, v19
	v_cvt_pk_bf16_f32 v11, v14, v15
	v_cvt_pk_bf16_f32 v12, v20, v21
	v_cvt_pk_bf16_f32 v13, v16, v17
	v_addc_co_u32_e32 v31, vcc, 0, v87, vcc
	global_store_dwordx4 v[30:31], v[10:13], off
	s_lshl_b64 s[8:9], s[0:1], 18
	s_add_u32 s8, s50, s8
	v_cvt_pk_bf16_f32 v10, v22, v23
	v_cvt_pk_bf16_f32 v11, v24, v25
	v_cvt_pk_bf16_f32 v12, v26, v27
	v_cvt_pk_bf16_f32 v13, v28, v29
	global_store_dwordx4 v[30:31], v[10:13], off offset:512
	s_addc_u32 s9, s51, s9
	s_lshl_b32 s6, s6, 7
	v_lshlrev_b32_e32 v10, 16, v6
	v_lshlrev_b32_e32 v11, 16, v7
	v_mul_f32_e32 v10, v53, v10
	v_and_b32_e32 v6, 0xffff0000, v6
	v_mul_f32_e32 v11, v53, v11
	v_and_b32_e32 v7, 0xffff0000, v7
	v_fmac_f32_e32 v10, v18, v49
	v_mul_f32_e32 v6, v53, v6
	v_fmac_f32_e32 v11, v14, v49
	v_mul_f32_e32 v7, v53, v7
	v_lshlrev_b32_e32 v12, 16, v8
	v_and_b32_e32 v8, 0xffff0000, v8
	v_lshlrev_b32_e32 v13, 16, v9
	v_and_b32_e32 v9, 0xffff0000, v9
	v_lshlrev_b32_e32 v14, 16, v2
	v_and_b32_e32 v2, 0xffff0000, v2
	v_mul_u32_u24_e32 v18, 0x84, v85
	v_fmac_f32_e32 v6, v19, v49
	v_fmac_f32_e32 v7, v15, v49
	v_mul_f32_e32 v12, v53, v12
	v_mul_f32_e32 v8, v53, v8
	v_mul_f32_e32 v13, v53, v13
	v_mul_f32_e32 v9, v53, v9
	v_mul_f32_e32 v2, v53, v2
	v_lshlrev_b32_e32 v15, 16, v3
	v_and_b32_e32 v3, 0xffff0000, v3
	v_add3_u32 v1, 0, v1, v18
	v_fmac_f32_e32 v12, v20, v49
	v_fmac_f32_e32 v8, v21, v49
	v_fmac_f32_e32 v13, v16, v49
	v_fmac_f32_e32 v9, v17, v49
	v_mul_f32_e32 v14, v53, v14
	v_fmac_f32_e32 v2, v23, v49
	v_mul_f32_e32 v15, v53, v15
	v_mul_f32_e32 v3, v53, v3
	v_lshlrev_b32_e32 v16, 16, v4
	v_and_b32_e32 v4, 0xffff0000, v4
	v_lshlrev_b32_e32 v17, 16, v5
	v_and_b32_e32 v5, 0xffff0000, v5
	ds_write2_b32 v1, v10, v6 offset0:128 offset1:161
	ds_write2_b32 v1, v11, v7 offset0:194 offset1:227
	v_add_u32_e32 v6, 0x400, v1
	v_fmac_f32_e32 v14, v22, v49
	v_fmac_f32_e32 v15, v24, v49
	v_fmac_f32_e32 v3, v25, v49
	v_mul_f32_e32 v16, v53, v16
	v_mul_f32_e32 v4, v53, v4
	v_mul_f32_e32 v5, v53, v5
	ds_write2_b32 v6, v12, v8 offset0:4 offset1:37
	ds_write2_b32 v6, v13, v9 offset0:70 offset1:103
	ds_write2_b32 v6, v14, v2 offset0:136 offset1:169
	ds_write2_b32 v6, v15, v3 offset0:202 offset1:235
	v_ashrrev_i32_e32 v2, 1, v84
	v_fmac_f32_e32 v16, v26, v49
	v_fmac_f32_e32 v4, v27, v49
	v_mul_f32_e32 v17, v53, v17
	v_fmac_f32_e32 v5, v29, v49
	v_add_u32_e32 v1, 0x800, v1
	v_ashrrev_i32_e32 v3, 31, v2
	v_fmac_f32_e32 v17, v28, v49
	ds_write2_b32 v1, v16, v4 offset0:12 offset1:45
	ds_write2_b32 v1, v17, v5 offset0:78 offset1:111
	v_lshlrev_b64 v[4:5], 10, v[2:3]
	v_lshlrev_b32_e32 v1, 6, v84
	v_lshl_add_u64 v[4:5], s[8:9], 0, v[4:5]
	v_and_b32_e32 v82, 64, v1
	v_mul_lo_u32 v1, v2, s10
	v_lshl_add_u64 v[4:5], v[4:5], 0, s[6:7]
	v_add3_u32 v1, 0, v1, v82
	s_waitcnt lgkmcnt(0)
	s_barrier
	v_lshl_add_u64 v[18:19], v[4:5], 0, v[82:83]
	s_mov_b64 s[6:7], 0x4080000
	s_mov_b32 s1, 0x4080000
	ds_read2_b32 v[2:3], v1 offset0:128 offset1:129
	ds_read2_b32 v[4:5], v1 offset0:130 offset1:131
	ds_read2_b32 v[6:7], v1 offset0:132 offset1:133
	ds_read2_b32 v[8:9], v1 offset0:134 offset1:135
	ds_read2_b32 v[10:11], v1 offset0:136 offset1:137
	ds_read2_b32 v[12:13], v1 offset0:138 offset1:139
	ds_read2_b32 v[14:15], v1 offset0:140 offset1:141
	ds_read2_b32 v[16:17], v1 offset0:142 offset1:143
	v_lshl_add_u64 v[20:21], v[18:19], 0, s[6:7]
	v_add_co_u32_e32 v18, vcc, s1, v18
	s_movk_i32 s1, 0x100
	s_nop 0
	v_addc_co_u32_e32 v19, vcc, 0, v19, vcc
	v_cmp_gt_i32_e32 vcc, s1, v84
	s_and_b64 s[6:7], s[2:3], vcc
	s_waitcnt lgkmcnt(6)
	global_store_dwordx4 v[18:19], v[2:5], off
	s_waitcnt lgkmcnt(4)
	global_store_dwordx4 v[20:21], v[6:9], off offset:16
	s_waitcnt lgkmcnt(2)
	global_store_dwordx4 v[20:21], v[10:13], off offset:32
	s_waitcnt lgkmcnt(0)
	global_store_dwordx4 v[20:21], v[14:17], off offset:48
	s_and_saveexec_b64 s[2:3], s[6:7]
	s_cbranch_execz .LBB0_958
	s_lshl_b64 s[4:5], s[4:5], 2
	v_ashrrev_i32_e32 v85, 31, v84
	s_add_u32 s4, s96, s4
	v_lshlrev_b64 v[2:3], 2, v[84:85]
	s_addc_u32 s5, s97, s5
	v_lshl_add_u64 v[4:5], s[4:5], 0, v[2:3]
	v_add_co_u32_e32 v8, vcc, 0x2bb80000, v4
	s_mov_b64 s[4:5], 0x2bb80000
	s_nop 0
	v_addc_co_u32_e32 v9, vcc, 0, v5, vcc
	v_add_co_u32_e32 v10, vcc, 0x2bb81000, v4
	v_lshl_add_u64 v[6:7], v[4:5], 0, s[4:5]
	s_nop 0
	v_addc_co_u32_e32 v11, vcc, 0, v5, vcc
	global_load_dword v23, v[8:9], off
	global_load_dword v1, v[6:7], off offset:1024
	global_load_dword v40, v[6:7], off offset:2048
	global_load_dword v41, v[10:11], off
	global_load_dword v42, v[10:11], off offset:1024
	global_load_dword v43, v[10:11], off offset:2048
	global_load_dword v44, v[10:11], off offset:3072
	global_load_dword v45, v[6:7], off offset:3072
	v_add_co_u32_e32 v24, vcc, 0x2bb82000, v4
	s_mov_b32 s1, 0x2bc01000
	s_nop 0
	v_addc_co_u32_e32 v25, vcc, 0, v5, vcc
	global_load_dword v46, v[24:25], off
	ds_read_b128 v[6:9], v83
	ds_read_b128 v[10:13], v83 offset:16
	ds_read_b128 v[14:17], v83 offset:64
	ds_read_b128 v[18:21], v83 offset:80
	global_load_dword v47, v[24:25], off offset:1024
	global_load_dword v48, v[24:25], off offset:2048
	global_load_dword v49, v[24:25], off offset:3072
	v_add_co_u32_e32 v28, vcc, s1, v4
	s_mov_b32 s6, 0x2bc02000
	s_nop 0
	v_addc_co_u32_e32 v29, vcc, 0, v5, vcc
	v_add_co_u32_e32 v30, vcc, s6, v4
	v_mov_b32_e32 v22, v83
	s_nop 0
	v_addc_co_u32_e32 v31, vcc, 0, v5, vcc
	v_add_co_u32_e32 v34, vcc, 0x2bb83000, v4
	s_waitcnt lgkmcnt(2)
	v_mov_b32_e32 v36, v10
	v_addc_co_u32_e32 v35, vcc, 0, v5, vcc
	global_load_dword v50, v[34:35], off
	global_load_dword v51, v[34:35], off offset:1024
	global_load_dword v52, v[34:35], off offset:2048
	global_load_dword v53, v[34:35], off offset:3072
	v_mov_b32_e32 v24, v6
	s_waitcnt lgkmcnt(1)
	v_mov_b32_e32 v25, v14
	s_mov_b64 s[4:5], 0x2bc00000
	v_lshl_add_u64 v[26:27], v[4:5], 0, s[4:5]
	v_mov_b32_e32 v32, v8
	v_mov_b32_e32 v33, v16
	s_waitcnt lgkmcnt(0)
	v_mov_b32_e32 v37, v18
	v_add_co_u32_e32 v38, vcc, 0x2bc00000, v4
	s_mov_b32 s1, 0x2bc03000
	s_nop 0
	v_addc_co_u32_e32 v39, vcc, 0, v5, vcc
	v_add_co_u32_e32 v4, vcc, s1, v4
	s_lshl_b32 s0, s0, 8
	s_nop 0
	v_addc_co_u32_e32 v5, vcc, 0, v5, vcc
	s_ashr_i32 s1, s0, 31
	s_lshl_b64 s[0:1], s[0:1], 2
	s_add_u32 s0, s50, s0
	s_addc_u32 s1, s51, s1
	v_lshl_add_u64 v[2:3], s[0:1], 0, v[2:3]
	v_add_co_u32_e32 v2, vcc, 0x4880000, v2
	global_store_dword v[38:39], v83, off
	s_nop 0
	v_addc_co_u32_e32 v3, vcc, 0, v3, vcc
	s_waitcnt vmcnt(16)
	v_mul_f32_e32 v10, v14, v23
	v_pk_fma_f32 v[22:23], v[24:25], v[22:23], v[10:11] op_sel_hi:[1,1,0]
	s_waitcnt vmcnt(15)
	v_mul_f32_e32 v6, v1, v15
	v_mov_b32_e32 v14, v7
	v_mov_b32_e32 v23, v1
	v_pk_fma_f32 v[6:7], v[22:23], v[14:15], v[6:7] op_sel_hi:[1,1,0]
	s_waitcnt vmcnt(14)
	v_mul_f32_e32 v8, v40, v16
	v_mov_b32_e32 v7, v40
	global_store_dword v[26:27], v6, off offset:2048
	v_pk_fma_f32 v[6:7], v[6:7], v[32:33], v[8:9] op_sel_hi:[1,1,0]
	v_mov_b32_e32 v16, v9
	s_waitcnt vmcnt(10)
	v_mul_f32_e32 v10, v45, v17
	v_mov_b32_e32 v7, v45
	global_store_dword v[26:27], v6, off offset:3072
	v_pk_fma_f32 v[6:7], v[6:7], v[16:17], v[10:11] op_sel_hi:[1,1,0]
	v_mul_f32_e32 v18, v41, v18
	v_mov_b32_e32 v7, v41
	global_store_dword v[30:31], v6, off offset:-4096
	v_pk_fma_f32 v[6:7], v[6:7], v[36:37], v[18:19] op_sel_hi:[1,1,0]
	v_mov_b32_e32 v18, v11
	v_mov_b32_e32 v7, v42
	v_mul_f32_e32 v8, v42, v19
	global_store_dword v[28:29], v6, off offset:1024
	v_pk_fma_f32 v[6:7], v[6:7], v[18:19], v[8:9] op_sel_hi:[1,1,0]
	v_mov_b32_e32 v8, v12
	v_mov_b32_e32 v7, v43
	v_mov_b32_e32 v9, v20
	v_mul_f32_e32 v10, v43, v20
	global_store_dword v[28:29], v6, off offset:2048
	v_pk_fma_f32 v[6:7], v[6:7], v[8:9], v[10:11] op_sel_hi:[1,1,0]
	v_mov_b32_e32 v20, v13
	v_mov_b32_e32 v7, v44
	v_mul_f32_e32 v8, v44, v21
	global_store_dword v[26:27], v22, off offset:1024
	global_store_dword v[28:29], v6, off offset:3072
	v_pk_fma_f32 v[22:23], v[6:7], v[20:21], v[8:9] op_sel_hi:[1,1,0]
	ds_read_b128 v[6:9], v83 offset:32
	ds_read_b128 v[14:17], v83 offset:48
	ds_read_b128 v[10:13], v83 offset:96
	ds_read_b128 v[18:21], v83 offset:112
	s_waitcnt vmcnt(15)
	v_mov_b32_e32 v23, v46
	s_waitcnt lgkmcnt(3)
	v_mov_b32_e32 v24, v6
	global_store_dword v[30:31], v22, off
	s_waitcnt lgkmcnt(1)
	v_mov_b32_e32 v25, v10
	v_mul_f32_e32 v6, v46, v10
	v_pk_fma_f32 v[22:23], v[22:23], v[24:25], v[6:7] op_sel_hi:[1,1,0]
	v_mov_b32_e32 v10, v7
	s_waitcnt vmcnt(15)
	v_mov_b32_e32 v23, v47
	v_mul_f32_e32 v6, v47, v11
	v_pk_fma_f32 v[6:7], v[22:23], v[10:11], v[6:7] op_sel_hi:[1,1,0]
	v_mov_b32_e32 v10, v8
	s_waitcnt vmcnt(14)
	v_mov_b32_e32 v7, v48
	v_mov_b32_e32 v11, v12
	v_mul_f32_e32 v8, v48, v12
	global_store_dword v[30:31], v6, off offset:2048
	v_pk_fma_f32 v[6:7], v[6:7], v[10:11], v[8:9] op_sel_hi:[1,1,0]
	v_mov_b32_e32 v12, v9
	s_waitcnt vmcnt(14)
	v_mov_b32_e32 v7, v49
	v_mul_f32_e32 v8, v49, v13
	global_store_dword v[30:31], v6, off offset:3072
	v_pk_fma_f32 v[6:7], v[6:7], v[12:13], v[8:9] op_sel_hi:[1,1,0]
	v_mov_b32_e32 v8, v14
	s_waitcnt vmcnt(14)
	v_mov_b32_e32 v7, v50
	s_waitcnt lgkmcnt(0)
	v_mov_b32_e32 v9, v18
	v_mul_f32_e32 v10, v50, v18
	global_store_dword v[4:5], v6, off
	v_pk_fma_f32 v[6:7], v[6:7], v[8:9], v[10:11] op_sel_hi:[1,1,0]
	v_mov_b32_e32 v18, v15
	s_waitcnt vmcnt(14)
	v_mov_b32_e32 v7, v51
	v_mul_f32_e32 v8, v51, v19
	global_store_dword v[4:5], v6, off offset:1024
	v_pk_fma_f32 v[6:7], v[6:7], v[18:19], v[8:9] op_sel_hi:[1,1,0]
	v_mov_b32_e32 v8, v16
	s_waitcnt vmcnt(14)
	v_mov_b32_e32 v7, v52
	v_mov_b32_e32 v9, v20
	v_mul_f32_e32 v10, v52, v20
	global_store_dword v[4:5], v6, off offset:2048
	v_pk_fma_f32 v[6:7], v[6:7], v[8:9], v[10:11] op_sel_hi:[1,1,0]
	v_mov_b32_e32 v20, v17
	s_waitcnt vmcnt(14)
	v_mov_b32_e32 v7, v53
	global_store_dword v[4:5], v6, off offset:3072
	v_pk_mul_f32 v[4:5], v[6:7], v[20:21]
	global_store_dword v[30:31], v22, off offset:1024
	v_add_f32_e32 v1, v4, v5
	global_store_dword v[2:3], v1, off
